# grid barrier: non-leader workgroups poll the cross-XCC release generation directly instead of the per-XCC word (one hop less)
# speedup vs baseline: 1.1140x; 1.0035x over previous
; __device__ __forceinline__ unsigned xb_ld(unsigned* p)              { return __hip_atomic_load(p, __ATOMIC_RELAXED, __HIP_MEMORY_SCOPE_AGENT); }
; __device__ __forceinline__ unsigned xb_add(unsigned* p, unsigned v) { return __hip_atomic_fetch_add(p, v, __ATOMIC_RELAXED, __HIP_MEMORY_SCOPE_AGENT); }
; #define XB_SPIN(cond, bar) do { unsigned _sp = 0; while (cond) { __builtin_amdgcn_s_sleep(1); \
;     if ((++_sp & 255u) == 0u) { if (xb_ld(&(bar)[XB_TMO])) break; if (_sp > XB_SPIN_CAP) { atomicAdd(&(bar)[XB_TMO], 1u); break; } } } } while (0)
; __device__ __forceinline__ void xcd_barrier(const XcdBarrier& b) {
;     ...
;         const unsigned old = xb_add(&bar[XB_XSUB(b.x)], 1u);
;         const unsigned gen = old / nloc;
;         if (old + 1u == (gen + 1u) * nloc) {
;             __builtin_amdgcn_fence(__ATOMIC_RELEASE, "agent");
;             asm volatile("s_waitcnt vmcnt(0)" ::: "memory");
;             const unsigned og = xb_add(&bar[XB_TOP], 1u);
;             const unsigned tg = og / nx;
;             if (og + 1u == (tg + 1u) * nx) xb_add(&bar[XB_TOPGEN], 1u);
;             else XB_SPIN(xb_ld(&bar[XB_TOPGEN]) == tg, bar);
;             __builtin_amdgcn_fence(__ATOMIC_ACQUIRE, "agent");
;             xb_add(&bar[XB_XGEN(b.x)], 1u);
;             asm volatile("s_waitcnt vmcnt(0)" ::: "memory");
;         } else {
;             XB_SPIN(xb_ld(&bar[XB_XGEN(b.x)]) == gen, bar);
.LBB0_70:
	s_or_b64 exec, exec, s[10:11]
	v_cvt_f32_u32_e32 v4, v2
	s_waitcnt vmcnt(0)
	buffer_inv sc1
	v_readfirstlane_b32 s0, v3
	v_sub_u32_e32 v3, 0, v2
	v_rcp_iflag_f32_e32 v4, v4
	v_add_u32_e32 v5, s0, v1
	v_mul_f32_e32 v4, 0x4f7ffffe, v4
	v_cvt_u32_f32_e32 v4, v4
	v_mul_lo_u32 v1, v3, v4
	v_mul_hi_u32 v1, v4, v1
	v_add_u32_e32 v1, v4, v1
	v_mul_hi_u32 v1, v5, v1
	v_mul_lo_u32 v3, v1, v2
	v_sub_u32_e32 v3, v5, v3
	v_add_u32_e32 v4, 1, v1
	v_cmp_ge_u32_e32 vcc, v3, v2
	s_nop 1
	v_cndmask_b32_e32 v1, v1, v4, vcc
	v_sub_u32_e32 v4, v3, v2
	v_cndmask_b32_e32 v3, v3, v4, vcc
	v_add_u32_e32 v4, 1, v1
	v_cmp_ge_u32_e32 vcc, v3, v2
	v_add_u32_e32 v3, 1, v5
	s_nop 0
	v_cndmask_b32_e32 v1, v1, v4, vcc
	v_mul_lo_u32 v4, v2, v1
	v_add_u32_e32 v2, v4, v2
	v_cmp_ne_u32_e32 vcc, v3, v2
	s_and_saveexec_b64 s[0:1], vcc
	s_xor_b64 s[10:11], exec, s[0:1]
	s_cbranch_execz .LBB0_84
	s_waitcnt lgkmcnt(0)
	v_mov_b32_e32 v0, 0
	s_add_u32 s14, s90, 0x10bd5d00
	s_addc_u32 s15, s91, 0
	global_load_dword v0, v0, s[14:15] sc1
	s_waitcnt vmcnt(0)
	v_cmp_eq_u32_e32 vcc, v0, v1
	s_and_saveexec_b64 s[4:5], vcc
	s_cbranch_execz .LBB0_83
	s_add_u32 s12, s90, 0x10bd2a00
	s_addc_u32 s13, s91, 0
	s_mov_b32 s0, 1
	s_mov_b64 s[16:17], 0
	v_mov_b32_e32 v0, 0
	s_branch .LBB0_74

; __device__ __forceinline__ unsigned xb_ld(unsigned* p)              { return __hip_atomic_load(p, __ATOMIC_RELAXED, __HIP_MEMORY_SCOPE_AGENT); }
; __device__ __forceinline__ unsigned xb_add(unsigned* p, unsigned v) { return __hip_atomic_fetch_add(p, v, __ATOMIC_RELAXED, __HIP_MEMORY_SCOPE_AGENT); }
; #define XB_SPIN(cond, bar) do { unsigned _sp = 0; while (cond) { __builtin_amdgcn_s_sleep(1); \
;     if ((++_sp & 255u) == 0u) { if (xb_ld(&(bar)[XB_TMO])) break; if (_sp > XB_SPIN_CAP) { atomicAdd(&(bar)[XB_TMO], 1u); break; } } } } while (0)
; __device__ __forceinline__ void xcd_barrier(const XcdBarrier& b) {
;     ...
;         const unsigned old = xb_add(&bar[XB_XSUB(b.x)], 1u);
;         const unsigned gen = old / nloc;
;         if (old + 1u == (gen + 1u) * nloc) {
;             __builtin_amdgcn_fence(__ATOMIC_RELEASE, "agent");
;             asm volatile("s_waitcnt vmcnt(0)" ::: "memory");
;             const unsigned og = xb_add(&bar[XB_TOP], 1u);
;             const unsigned tg = og / nx;
;             if (og + 1u == (tg + 1u) * nx) xb_add(&bar[XB_TOPGEN], 1u);
;             else XB_SPIN(xb_ld(&bar[XB_TOPGEN]) == tg, bar);
;             __builtin_amdgcn_fence(__ATOMIC_ACQUIRE, "agent");
;             xb_add(&bar[XB_XGEN(b.x)], 1u);
;             asm volatile("s_waitcnt vmcnt(0)" ::: "memory");
;         } else {
;             XB_SPIN(xb_ld(&bar[XB_XGEN(b.x)]) == gen, bar);
.LBB0_634:
	s_or_b64 exec, exec, s[8:9]
	v_cvt_f32_u32_e32 v4, v2
	s_waitcnt vmcnt(0)
	buffer_inv sc1
	v_readfirstlane_b32 s4, v3
	v_sub_u32_e32 v3, 0, v2
	v_rcp_iflag_f32_e32 v4, v4
	v_add_u32_e32 v5, s4, v1
	v_mul_f32_e32 v4, 0x4f7ffffe, v4
	v_cvt_u32_f32_e32 v4, v4
	v_mul_lo_u32 v1, v3, v4
	v_mul_hi_u32 v1, v4, v1
	v_add_u32_e32 v1, v4, v1
	v_mul_hi_u32 v1, v5, v1
	v_mul_lo_u32 v3, v1, v2
	v_sub_u32_e32 v3, v5, v3
	v_add_u32_e32 v4, 1, v1
	v_cmp_ge_u32_e32 vcc, v3, v2
	s_nop 1
	v_cndmask_b32_e32 v1, v1, v4, vcc
	v_sub_u32_e32 v4, v3, v2
	v_cndmask_b32_e32 v3, v3, v4, vcc
	v_add_u32_e32 v4, 1, v1
	v_cmp_ge_u32_e32 vcc, v3, v2
	v_add_u32_e32 v3, 1, v5
	s_nop 0
	v_cndmask_b32_e32 v1, v1, v4, vcc
	v_mul_lo_u32 v4, v2, v1
	v_add_u32_e32 v2, v4, v2
	v_cmp_ne_u32_e32 vcc, v3, v2
	s_and_saveexec_b64 s[4:5], vcc
	s_xor_b64 s[8:9], exec, s[4:5]
	s_cbranch_execz .LBB0_648
	s_waitcnt lgkmcnt(0)
	v_mov_b32_e32 v0, 0
	s_add_u32 s20, s90, 0x10bd5d00
	s_addc_u32 s21, s91, 0
	global_load_dword v0, v0, s[20:21] sc1
	s_waitcnt vmcnt(0)
	v_cmp_eq_u32_e32 vcc, v0, v1
	s_and_saveexec_b64 s[4:5], vcc
	s_cbranch_execz .LBB0_647
	s_add_u32 s14, s90, 0x10bd2a00
	s_addc_u32 s15, s91, 0
	s_mov_b32 s10, 1
	s_mov_b64 s[24:25], 0
	v_mov_b32_e32 v0, 0
	s_branch .LBB0_638

; __device__ __forceinline__ unsigned xb_ld(unsigned* p)              { return __hip_atomic_load(p, __ATOMIC_RELAXED, __HIP_MEMORY_SCOPE_AGENT); }
; __device__ __forceinline__ unsigned xb_add(unsigned* p, unsigned v) { return __hip_atomic_fetch_add(p, v, __ATOMIC_RELAXED, __HIP_MEMORY_SCOPE_AGENT); }
; #define XB_SPIN(cond, bar) do { unsigned _sp = 0; while (cond) { __builtin_amdgcn_s_sleep(1); \
;     if ((++_sp & 255u) == 0u) { if (xb_ld(&(bar)[XB_TMO])) break; if (_sp > XB_SPIN_CAP) { atomicAdd(&(bar)[XB_TMO], 1u); break; } } } } while (0)
; __device__ __forceinline__ void xcd_barrier(const XcdBarrier& b) {
;     ...
;         const unsigned old = xb_add(&bar[XB_XSUB(b.x)], 1u);
;         const unsigned gen = old / nloc;
;         if (old + 1u == (gen + 1u) * nloc) {
;             __builtin_amdgcn_fence(__ATOMIC_RELEASE, "agent");
;             asm volatile("s_waitcnt vmcnt(0)" ::: "memory");
;             const unsigned og = xb_add(&bar[XB_TOP], 1u);
;             const unsigned tg = og / nx;
;             if (og + 1u == (tg + 1u) * nx) xb_add(&bar[XB_TOPGEN], 1u);
;             else XB_SPIN(xb_ld(&bar[XB_TOPGEN]) == tg, bar);
;             __builtin_amdgcn_fence(__ATOMIC_ACQUIRE, "agent");
;             xb_add(&bar[XB_XGEN(b.x)], 1u);
;             asm volatile("s_waitcnt vmcnt(0)" ::: "memory");
;         } else {
;             XB_SPIN(xb_ld(&bar[XB_XGEN(b.x)]) == gen, bar);
.LBB0_910:
	s_or_b64 exec, exec, s[8:9]
	v_cvt_f32_u32_e32 v4, v2
	s_waitcnt vmcnt(0)
	buffer_inv sc1
	v_readfirstlane_b32 s4, v3
	v_sub_u32_e32 v3, 0, v2
	v_rcp_iflag_f32_e32 v4, v4
	v_add_u32_e32 v5, s4, v1
	v_mul_f32_e32 v4, 0x4f7ffffe, v4
	v_cvt_u32_f32_e32 v4, v4
	v_mul_lo_u32 v1, v3, v4
	v_mul_hi_u32 v1, v4, v1
	v_add_u32_e32 v1, v4, v1
	v_mul_hi_u32 v1, v5, v1
	v_mul_lo_u32 v3, v1, v2
	v_sub_u32_e32 v3, v5, v3
	v_add_u32_e32 v4, 1, v1
	v_cmp_ge_u32_e32 vcc, v3, v2
	s_nop 1
	v_cndmask_b32_e32 v1, v1, v4, vcc
	v_sub_u32_e32 v4, v3, v2
	v_cndmask_b32_e32 v3, v3, v4, vcc
	v_add_u32_e32 v4, 1, v1
	v_cmp_ge_u32_e32 vcc, v3, v2
	v_add_u32_e32 v3, 1, v5
	s_nop 0
	v_cndmask_b32_e32 v1, v1, v4, vcc
	v_mul_lo_u32 v4, v2, v1
	v_add_u32_e32 v2, v4, v2
	v_cmp_ne_u32_e32 vcc, v3, v2
	s_and_saveexec_b64 s[4:5], vcc
	s_xor_b64 s[8:9], exec, s[4:5]
	s_cbranch_execz .LBB0_924
	s_waitcnt lgkmcnt(0)
	v_mov_b32_e32 v0, 0
	s_add_u32 s30, s90, 0x10bd5d00
	s_addc_u32 s31, s91, 0
	global_load_dword v0, v0, s[30:31] sc1
	s_waitcnt vmcnt(0)
	v_cmp_eq_u32_e32 vcc, v0, v1
	s_and_saveexec_b64 s[4:5], vcc
	s_cbranch_execz .LBB0_923
	s_add_u32 s12, s90, 0x10bd2a00
	s_addc_u32 s13, s91, 0
	s_mov_b32 s10, 1
	s_mov_b64 s[40:41], 0
	v_mov_b32_e32 v0, 0
	s_branch .LBB0_914

; __device__ __forceinline__ unsigned xb_ld(unsigned* p)              { return __hip_atomic_load(p, __ATOMIC_RELAXED, __HIP_MEMORY_SCOPE_AGENT); }
; __device__ __forceinline__ unsigned xb_add(unsigned* p, unsigned v) { return __hip_atomic_fetch_add(p, v, __ATOMIC_RELAXED, __HIP_MEMORY_SCOPE_AGENT); }
; #define XB_SPIN(cond, bar) do { unsigned _sp = 0; while (cond) { __builtin_amdgcn_s_sleep(1); \
;     if ((++_sp & 255u) == 0u) { if (xb_ld(&(bar)[XB_TMO])) break; if (_sp > XB_SPIN_CAP) { atomicAdd(&(bar)[XB_TMO], 1u); break; } } } } while (0)
; __device__ __forceinline__ void xcd_barrier(const XcdBarrier& b) {
;     ...
;         const unsigned old = xb_add(&bar[XB_XSUB(b.x)], 1u);
;         const unsigned gen = old / nloc;
;         if (old + 1u == (gen + 1u) * nloc) {
;             __builtin_amdgcn_fence(__ATOMIC_RELEASE, "agent");
;             asm volatile("s_waitcnt vmcnt(0)" ::: "memory");
;             const unsigned og = xb_add(&bar[XB_TOP], 1u);
;             const unsigned tg = og / nx;
;             if (og + 1u == (tg + 1u) * nx) xb_add(&bar[XB_TOPGEN], 1u);
;             else XB_SPIN(xb_ld(&bar[XB_TOPGEN]) == tg, bar);
;             __builtin_amdgcn_fence(__ATOMIC_ACQUIRE, "agent");
;             xb_add(&bar[XB_XGEN(b.x)], 1u);
;             asm volatile("s_waitcnt vmcnt(0)" ::: "memory");
;         } else {
;             XB_SPIN(xb_ld(&bar[XB_XGEN(b.x)]) == gen, bar);
.LBB0_989:
	s_or_b64 exec, exec, s[8:9]
	v_cvt_f32_u32_e32 v4, v2
	s_waitcnt vmcnt(0)
	buffer_inv sc1
	v_readfirstlane_b32 s4, v3
	v_sub_u32_e32 v3, 0, v2
	v_rcp_iflag_f32_e32 v4, v4
	v_add_u32_e32 v5, s4, v1
	v_mul_f32_e32 v4, 0x4f7ffffe, v4
	v_cvt_u32_f32_e32 v4, v4
	v_mul_lo_u32 v1, v3, v4
	v_mul_hi_u32 v1, v4, v1
	v_add_u32_e32 v1, v4, v1
	v_mul_hi_u32 v1, v5, v1
	v_mul_lo_u32 v3, v1, v2
	v_sub_u32_e32 v3, v5, v3
	v_add_u32_e32 v4, 1, v1
	v_cmp_ge_u32_e32 vcc, v3, v2
	s_nop 1
	v_cndmask_b32_e32 v1, v1, v4, vcc
	v_sub_u32_e32 v4, v3, v2
	v_cndmask_b32_e32 v3, v3, v4, vcc
	v_add_u32_e32 v4, 1, v1
	v_cmp_ge_u32_e32 vcc, v3, v2
	v_add_u32_e32 v3, 1, v5
	s_nop 0
	v_cndmask_b32_e32 v1, v1, v4, vcc
	v_mul_lo_u32 v4, v2, v1
	v_add_u32_e32 v2, v4, v2
	v_cmp_ne_u32_e32 vcc, v3, v2
	s_and_saveexec_b64 s[4:5], vcc
	s_xor_b64 s[8:9], exec, s[4:5]
	s_cbranch_execz .LBB0_1003
	s_waitcnt lgkmcnt(0)
	v_mov_b32_e32 v0, 0
	s_add_u32 s12, s90, 0x10bd5d00
	s_addc_u32 s13, s91, 0
	global_load_dword v0, v0, s[12:13] sc1
	s_waitcnt vmcnt(0)
	v_cmp_eq_u32_e32 vcc, v0, v1
	s_and_saveexec_b64 s[4:5], vcc
	s_cbranch_execz .LBB0_1002
	s_add_u32 s10, s90, 0x10bd2a00
	s_addc_u32 s11, s91, 0
	s_mov_b32 s14, 1
	s_mov_b64 s[26:27], 0
	v_mov_b32_e32 v0, 0
	s_branch .LBB0_993

; __device__ __forceinline__ unsigned xb_ld(unsigned* p)              { return __hip_atomic_load(p, __ATOMIC_RELAXED, __HIP_MEMORY_SCOPE_AGENT); }
; __device__ __forceinline__ unsigned xb_add(unsigned* p, unsigned v) { return __hip_atomic_fetch_add(p, v, __ATOMIC_RELAXED, __HIP_MEMORY_SCOPE_AGENT); }
; #define XB_SPIN(cond, bar) do { unsigned _sp = 0; while (cond) { __builtin_amdgcn_s_sleep(1); \
;     if ((++_sp & 255u) == 0u) { if (xb_ld(&(bar)[XB_TMO])) break; if (_sp > XB_SPIN_CAP) { atomicAdd(&(bar)[XB_TMO], 1u); break; } } } } while (0)
; __device__ __forceinline__ void xcd_barrier(const XcdBarrier& b) {
;     ...
;         const unsigned old = xb_add(&bar[XB_XSUB(b.x)], 1u);
;         const unsigned gen = old / nloc;
;         if (old + 1u == (gen + 1u) * nloc) {
;             __builtin_amdgcn_fence(__ATOMIC_RELEASE, "agent");
;             asm volatile("s_waitcnt vmcnt(0)" ::: "memory");
;             const unsigned og = xb_add(&bar[XB_TOP], 1u);
;             const unsigned tg = og / nx;
;             if (og + 1u == (tg + 1u) * nx) xb_add(&bar[XB_TOPGEN], 1u);
;             else XB_SPIN(xb_ld(&bar[XB_TOPGEN]) == tg, bar);
;             __builtin_amdgcn_fence(__ATOMIC_ACQUIRE, "agent");
;             xb_add(&bar[XB_XGEN(b.x)], 1u);
;             asm volatile("s_waitcnt vmcnt(0)" ::: "memory");
;         } else {
;             XB_SPIN(xb_ld(&bar[XB_XGEN(b.x)]) == gen, bar);
.LBB0_1158:
	s_or_b64 exec, exec, s[8:9]
	v_cvt_f32_u32_e32 v4, v2
	s_waitcnt vmcnt(0)
	buffer_inv sc1
	v_readfirstlane_b32 s4, v3
	v_sub_u32_e32 v3, 0, v2
	v_rcp_iflag_f32_e32 v4, v4
	v_add_u32_e32 v5, s4, v1
	v_mul_f32_e32 v4, 0x4f7ffffe, v4
	v_cvt_u32_f32_e32 v4, v4
	v_mul_lo_u32 v1, v3, v4
	v_mul_hi_u32 v1, v4, v1
	v_add_u32_e32 v1, v4, v1
	v_mul_hi_u32 v1, v5, v1
	v_mul_lo_u32 v3, v1, v2
	v_sub_u32_e32 v3, v5, v3
	v_add_u32_e32 v4, 1, v1
	v_cmp_ge_u32_e32 vcc, v3, v2
	s_nop 1
	v_cndmask_b32_e32 v1, v1, v4, vcc
	v_sub_u32_e32 v4, v3, v2
	v_cndmask_b32_e32 v3, v3, v4, vcc
	v_add_u32_e32 v4, 1, v1
	v_cmp_ge_u32_e32 vcc, v3, v2
	v_add_u32_e32 v3, 1, v5
	s_nop 0
	v_cndmask_b32_e32 v1, v1, v4, vcc
	v_mul_lo_u32 v4, v2, v1
	v_add_u32_e32 v2, v4, v2
	v_cmp_ne_u32_e32 vcc, v3, v2
	s_and_saveexec_b64 s[4:5], vcc
	s_xor_b64 s[8:9], exec, s[4:5]
	s_cbranch_execz .LBB0_1172
	s_waitcnt lgkmcnt(0)
	v_mov_b32_e32 v0, 0
	s_add_u32 s12, s90, 0x10bd5d00
	s_addc_u32 s13, s91, 0
	global_load_dword v0, v0, s[12:13] sc1
	s_waitcnt vmcnt(0)
	v_cmp_eq_u32_e32 vcc, v0, v1
	s_and_saveexec_b64 s[4:5], vcc
	s_cbranch_execz .LBB0_1171
	s_add_u32 s10, s90, 0x10bd2a00
	s_addc_u32 s11, s91, 0
	s_mov_b32 s14, 1
	s_mov_b64 s[16:17], 0
	v_mov_b32_e32 v0, 0
	s_branch .LBB0_1162

; __device__ __forceinline__ unsigned xb_ld(unsigned* p)              { return __hip_atomic_load(p, __ATOMIC_RELAXED, __HIP_MEMORY_SCOPE_AGENT); }
; __device__ __forceinline__ unsigned xb_add(unsigned* p, unsigned v) { return __hip_atomic_fetch_add(p, v, __ATOMIC_RELAXED, __HIP_MEMORY_SCOPE_AGENT); }
; #define XB_SPIN(cond, bar) do { unsigned _sp = 0; while (cond) { __builtin_amdgcn_s_sleep(1); \
;     if ((++_sp & 255u) == 0u) { if (xb_ld(&(bar)[XB_TMO])) break; if (_sp > XB_SPIN_CAP) { atomicAdd(&(bar)[XB_TMO], 1u); break; } } } } while (0)
; __device__ __forceinline__ void xcd_barrier(const XcdBarrier& b) {
;     ...
;         const unsigned old = xb_add(&bar[XB_XSUB(b.x)], 1u);
;         const unsigned gen = old / nloc;
;         if (old + 1u == (gen + 1u) * nloc) {
;             __builtin_amdgcn_fence(__ATOMIC_RELEASE, "agent");
;             asm volatile("s_waitcnt vmcnt(0)" ::: "memory");
;             const unsigned og = xb_add(&bar[XB_TOP], 1u);
;             const unsigned tg = og / nx;
;             if (og + 1u == (tg + 1u) * nx) xb_add(&bar[XB_TOPGEN], 1u);
;             else XB_SPIN(xb_ld(&bar[XB_TOPGEN]) == tg, bar);
;             __builtin_amdgcn_fence(__ATOMIC_ACQUIRE, "agent");
;             xb_add(&bar[XB_XGEN(b.x)], 1u);
;             asm volatile("s_waitcnt vmcnt(0)" ::: "memory");
;         } else {
;             XB_SPIN(xb_ld(&bar[XB_XGEN(b.x)]) == gen, bar);
.LBB0_1383:
	s_or_b64 exec, exec, s[8:9]
	v_cvt_f32_u32_e32 v4, v2
	s_waitcnt vmcnt(0)
	buffer_inv sc1
	v_readfirstlane_b32 s6, v3
	v_sub_u32_e32 v3, 0, v2
	v_rcp_iflag_f32_e32 v4, v4
	v_add_u32_e32 v5, s6, v1
	v_mul_f32_e32 v4, 0x4f7ffffe, v4
	v_cvt_u32_f32_e32 v4, v4
	v_mul_lo_u32 v1, v3, v4
	v_mul_hi_u32 v1, v4, v1
	v_add_u32_e32 v1, v4, v1
	v_mul_hi_u32 v1, v5, v1
	v_mul_lo_u32 v3, v1, v2
	v_sub_u32_e32 v3, v5, v3
	v_add_u32_e32 v4, 1, v1
	v_cmp_ge_u32_e32 vcc, v3, v2
	s_nop 1
	v_cndmask_b32_e32 v1, v1, v4, vcc
	v_sub_u32_e32 v4, v3, v2
	v_cndmask_b32_e32 v3, v3, v4, vcc
	v_add_u32_e32 v4, 1, v1
	v_cmp_ge_u32_e32 vcc, v3, v2
	v_add_u32_e32 v3, 1, v5
	s_nop 0
	v_cndmask_b32_e32 v1, v1, v4, vcc
	v_mul_lo_u32 v4, v2, v1
	v_add_u32_e32 v2, v4, v2
	v_cmp_ne_u32_e32 vcc, v3, v2
	s_and_saveexec_b64 s[6:7], vcc
	s_xor_b64 s[6:7], exec, s[6:7]
	s_cbranch_execz .LBB0_1397
	s_waitcnt lgkmcnt(0)
	v_mov_b32_e32 v0, 0
	s_add_u32 s12, s90, 0x10bd5d00
	s_addc_u32 s13, s91, 0
	global_load_dword v0, v0, s[12:13] sc1
	s_waitcnt vmcnt(0)
	v_cmp_eq_u32_e32 vcc, v0, v1
	s_and_saveexec_b64 s[8:9], vcc
	s_cbranch_execz .LBB0_1396
	s_add_u32 s10, s90, 0x10bd2a00
	s_addc_u32 s11, s91, 0
	s_mov_b32 s24, 1
	s_mov_b64 s[14:15], 0
	v_mov_b32_e32 v0, 0
	s_branch .LBB0_1387
